# mem_attn: K and V^T fragment gathers with a coalescing-friendly lane mapping (lane = 4*row + piece) + ds_bpermute into the MFMA A layout, fragments loaded 21 MFMAs ahead
# speedup vs baseline: 1.0083x; 1.0083x over previous
; __device__ __forceinline__ float ozero() { float z = 0.f; asm volatile("" : "+v"(z)); return z; }
; __device__ __forceinline__ int otid() { return otid_full() & 255; }
; __device__ __forceinline__ f32x4 mfma16(bf16x8 a, bf16x8 b, f32x4 c) { return __builtin_amdgcn_mfma_f32_16x16x32_bf16(a, b, c, 0, 0, 0); }
; __device__ __forceinline__ void mem_attn(const Params& p, int layer, int task) {
;   const int tid = otid(), lane = tid & 63, h = tid >> 6;
;   const int n16 = lane & 15, kq = lane >> 4;
;   const size_t tok0 = (size_t)task * 16; const int b = (int)(tok0 >> 14);
;   const bf* mk = p.MK + (((size_t)layer * 2 + b) * 4 + h) * 256 * 64;
;   const bf* mvt = p.MVT + (((size_t)layer * 2 + b) * 4 + h) * 64 * 256;
;   bf16x8 qf[2];
;   {
;     const bf* qp = p.P + (tok0 + n16) * PW + C_MEQ + h * 64 + 8 * kq;
;     qf[0] = *(const bf16x8*)qp; qf[1] = *(const bf16x8*)(qp + 32);
;   }
;   f32x4 st[16];
; #pragma unroll
;   for (int kb = 0; kb < 16; kb++) {
;     const bf* kp = mk + (size_t)(16 * kb + n16) * 64 + 8 * kq;
;     bf16x8 a0 = *(const bf16x8*)kp, a1 = *(const bf16x8*)(kp + 32);
;     const float z_ = ozero(); f32x4 acc = {z_, z_, z_, z_};
;     acc = mfma16(a0, qf[0], acc); acc = mfma16(a1, qf[1], acc);
;     st[kb] = acc * 0.125f;
;   }
.LBB0_472:
	s_cmpk_gt_i32 s31, 0x1ff
	s_mov_b64 s[0:1], -1
	s_cbranch_scc0 .LBB0_480
	s_cmpk_gt_u32 s31, 0x9ff
	s_cbranch_scc0 .LBB0_475
	s_add_i32 s0, s31, 0xfffff600
	s_lshr_b32 s1, s0, 8
	v_mov_b32_e32 v2, v203
	s_and_b32 s1, s1, 4
	s_or_b32 s1, s1, s27
	v_lshrrev_b32_e32 v0, 6, v2
	v_readlane_b32 s52, v253, 3
	v_and_b32_e32 v83, 15, v2
	v_and_or_b32 v0, v0, 3, s1
	v_readlane_b32 s62, v253, 13
	v_readlane_b32 s63, v253, 14
	v_bfe_u32 v3, v2, 4, 2
	v_lshlrev_b32_e32 v144, 15, v0
	v_lshl_or_b32 v82, s0, 4, v83
	v_mov_b64_e32 v[0:1], s[62:63]
	v_and_b32_e32 v2, 0xc0, v2
	v_readlane_b32 s4, v253, 22
	v_mad_u64_u32 v[0:1], s[0:1], v82, s96, v[0:1]
	v_lshlrev_b32_e32 v16, 1, v2
	v_mov_b32_e32 v17, v145
	v_readlane_b32 s6, v253, 24
	v_readlane_b32 s7, v253, 25
	v_lshlrev_b32_e32 v10, 4, v3
	v_mov_b32_e32 v11, v145
	v_lshl_add_u64 v[20:21], v[0:1], 0, v[16:17]
	v_lshl_add_u64 v[8:9], s[6:7], 0, v[144:145]
	v_lshl_add_u64 v[0:1], v[20:21], 0, v[10:11]
	s_mov_b64 s[0:1], 0x28c0
	s_movk_i32 s2, 0x2000
	v_lshlrev_b32_e32 v18, 3, v3
	v_lshl_add_u64 v[2:3], v[0:1], 0, s[0:1]
	v_add_co_u32_e32 v0, vcc, s2, v0
	v_lshl_add_u64 v[8:9], v[8:9], 0, v[10:11]
	v_lshlrev_b32_e32 v10, 7, v83
	v_addc_co_u32_e32 v1, vcc, 0, v1, vcc
	v_lshl_add_u64 v[8:9], v[8:9], 0, v[10:11]
	global_load_dwordx4 v[4:7], v[0:1], off offset:2240
	s_nop 0
	global_load_dwordx4 v[0:3], v[2:3], off offset:64
	s_nop 0
	v_and_b32_e32 v102, 15, v202
	v_lshrrev_b32_e32 v103, 4, v202
	v_lshlrev_b32_e32 v107, 2, v103
	v_lshl_or_b32 v107, v102, 4, v107
	v_lshlrev_b32_e32 v102, 7, v102
	v_lshl_add_u32 v102, v103, 4, v102
	v_lshrrev_b32_e32 v103, 2, v202
	v_lshlrev_b32_e32 v103, 7, v103
	v_sub_u32_e32 v102, v103, v102
	v_and_b32_e32 v103, 3, v202
	v_lshl_add_u32 v102, v103, 4, v102
	v_ashrrev_i32_e32 v103, 31, v102
	v_lshl_add_u64 v[104:105], v[8:9], 0, v[102:103]
	v_mov_b32_e32 v102, v104
	v_mov_b32_e32 v103, v105
	v_mov_b32_e32 v104, 0x1000
	v_mov_b32_e32 v105, 0
	v_lshl_add_u64 v[146:147], v[102:103], 0, v[104:105]
	v_mov_b32_e32 v104, 0x2000
	v_lshl_add_u64 v[196:197], v[146:147], 0, v[104:105]
	v_lshl_add_u64 v[198:199], v[196:197], 0, v[104:105]
	v_lshl_add_u64 v[200:201], v[198:199], 0, v[104:105]
	global_load_dwordx4 v[108:111], v[146:147], off offset:-4096
	global_load_dwordx4 v[112:115], v[146:147], off offset:-4032
	global_load_dwordx4 v[116:119], v[146:147], off offset:-2048
	global_load_dwordx4 v[120:123], v[146:147], off offset:-1984
	global_load_dwordx4 v[124:127], v[146:147], off
	global_load_dwordx4 v[128:131], v[146:147], off offset:64
	global_load_dwordx4 v[132:135], v[146:147], off offset:2048
	global_load_dwordx4 v[136:139], v[146:147], off offset:2112
	global_load_dwordx4 v[140:143], v[196:197], off offset:-4096
	global_load_dwordx4 v[148:151], v[196:197], off offset:-4032
	global_load_dwordx4 v[152:155], v[196:197], off offset:-2048
	global_load_dwordx4 v[156:159], v[196:197], off offset:-1984
	global_load_dwordx4 v[160:163], v[196:197], off
	global_load_dwordx4 v[164:167], v[196:197], off offset:64
	global_load_dwordx4 v[168:171], v[196:197], off offset:2048
	global_load_dwordx4 v[172:175], v[196:197], off offset:2112
	global_load_dwordx4 v[176:179], v[198:199], off offset:-4096
	global_load_dwordx4 v[180:183], v[198:199], off offset:-4032
	global_load_dwordx4 v[184:187], v[198:199], off offset:-2048
	global_load_dwordx4 v[188:191], v[198:199], off offset:-1984
	global_load_dwordx4 v[192:195], v[198:199], off
	v_mov_b32_e32 v26, v145
	s_mov_b32 s6, 0x3e000000
	v_mov_b32_e32 v27, v26
	v_mov_b32_e32 v28, v26
	v_mov_b32_e32 v29, v26
	v_mov_b32_e32 v32, v145
	s_movk_i32 s4, 0x1000
	v_add_co_u32_e32 v14, vcc, s4, v8
	v_mov_b32_e32 v38, v145
	s_nop 0
	v_addc_co_u32_e32 v15, vcc, 0, v9, vcc
	v_add_co_u32_e32 v48, vcc, s2, v8
	v_mov_b32_e32 v44, v145
	s_nop 0
	v_addc_co_u32_e32 v49, vcc, 0, v9, vcc
	s_movk_i32 s0, 0x3000
	v_add_co_u32_e32 v54, vcc, s0, v8
	s_movk_i32 s0, 0x4000
	s_nop 0
	v_addc_co_u32_e32 v55, vcc, 0, v9, vcc
	v_mov_b32_e32 v56, v145
	v_mov_b32_e32 v64, v145
	v_mov_b32_e32 v72, v145
	v_readlane_b32 s8, v253, 26
	v_readlane_b32 s9, v253, 27
	v_mov_b32_e32 v19, v145
	s_mov_b32 s3, 0xffff
	v_readlane_b32 s64, v253, 15
	v_readlane_b32 s65, v253, 16
	v_readlane_b32 s5, v253, 23
	v_readlane_b32 s10, v253, 28
	v_readlane_b32 s11, v253, 29
	v_readlane_b32 s12, v253, 30
	v_readlane_b32 s13, v253, 31
	v_readlane_b32 s14, v253, 32
	v_readlane_b32 s15, v253, 33
	v_readlane_b32 s16, v253, 34
	v_readlane_b32 s17, v253, 35
	v_readlane_b32 s18, v253, 36
	v_readlane_b32 s19, v253, 37
	v_readlane_b32 s53, v253, 4
	v_readlane_b32 s54, v253, 5
	v_readlane_b32 s55, v253, 6
	v_readlane_b32 s56, v253, 7
	s_waitcnt vmcnt(20)
	ds_bpermute_b32 v108, v107, v108
	ds_bpermute_b32 v109, v107, v109
	ds_bpermute_b32 v110, v107, v110
	ds_bpermute_b32 v111, v107, v111
	s_waitcnt lgkmcnt(0)
	v_mfma_f32_16x16x32_bf16 v[10:13], v[108:111], v[4:7], v[26:29]
	global_load_dwordx4 v[108:111], v[198:199], off offset:64
	v_readlane_b32 s57, v253, 8
	v_readlane_b32 s58, v253, 9
	v_readlane_b32 s59, v253, 10
	s_waitcnt vmcnt(20)
	ds_bpermute_b32 v112, v107, v112
	ds_bpermute_b32 v113, v107, v113
	ds_bpermute_b32 v114, v107, v114
	ds_bpermute_b32 v115, v107, v115
	s_waitcnt lgkmcnt(0)
	v_mfma_f32_16x16x32_bf16 v[10:13], v[112:115], v[0:3], v[10:13]
	global_load_dwordx4 v[112:115], v[198:199], off offset:2048
	v_readlane_b32 s60, v253, 11
	v_readlane_b32 s61, v253, 12
	v_readlane_b32 s66, v253, 17
	v_readlane_b32 s67, v253, 18
	s_nop 3
	v_pk_mul_f32 v[22:23], v[12:13], s[6:7] op_sel_hi:[1,0]
	v_pk_mul_f32 v[26:27], v[10:11], s[6:7] op_sel_hi:[1,0]
	s_nop 0
	v_mov_b32_e32 v33, v32
	v_mov_b32_e32 v34, v32
	v_mov_b32_e32 v35, v32
	s_nop 0
	s_waitcnt vmcnt(20)
; __device__ __forceinline__ float ozero() { float z = 0.f; asm volatile("" : "+v"(z)); return z; }
; __device__ __forceinline__ f32x4 mfma16(bf16x8 a, bf16x8 b, f32x4 c) { return __builtin_amdgcn_mfma_f32_16x16x32_bf16(a, b, c, 0, 0, 0); }
; __device__ __forceinline__ void mem_attn(const Params& p, int layer, int task) {
;     ...
; #pragma unroll
;   for (int kb = 0; kb < 16; kb++) {
;     const bf* kp = mk + (size_t)(16 * kb + n16) * 64 + 8 * kq;
;     bf16x8 a0 = *(const bf16x8*)kp, a1 = *(const bf16x8*)(kp + 32);
;     const float z_ = ozero(); f32x4 acc = {z_, z_, z_, z_};
;     acc = mfma16(a0, qf[0], acc); acc = mfma16(a1, qf[1], acc);
;     st[kb] = acc * 0.125f;
;   }
	ds_bpermute_b32 v116, v107, v116
	ds_bpermute_b32 v117, v107, v117
	ds_bpermute_b32 v118, v107, v118
	ds_bpermute_b32 v119, v107, v119
	s_waitcnt lgkmcnt(0)
	v_mfma_f32_16x16x32_bf16 v[10:13], v[116:119], v[4:7], v[32:35]
	global_load_dwordx4 v[116:119], v[198:199], off offset:2112
	s_nop 2
	v_mov_b32_e32 v34, v145
	s_waitcnt vmcnt(20)
	ds_bpermute_b32 v120, v107, v120
	ds_bpermute_b32 v121, v107, v121
	ds_bpermute_b32 v122, v107, v122
	ds_bpermute_b32 v123, v107, v123
	s_waitcnt lgkmcnt(0)
	v_mfma_f32_16x16x32_bf16 v[10:13], v[120:123], v[0:3], v[10:13]
	global_load_dwordx4 v[120:123], v[200:201], off offset:-4096
	s_nop 7
	v_pk_mul_f32 v[24:25], v[12:13], s[6:7] op_sel_hi:[1,0]
	v_pk_mul_f32 v[28:29], v[10:11], s[6:7] op_sel_hi:[1,0]
	s_nop 0
	v_mov_b32_e32 v35, v34
	v_mov_b32_e32 v36, v34
	v_mov_b32_e32 v37, v34
	s_nop 0
	s_waitcnt vmcnt(20)
	ds_bpermute_b32 v124, v107, v124
	ds_bpermute_b32 v125, v107, v125
	ds_bpermute_b32 v126, v107, v126
	ds_bpermute_b32 v127, v107, v127
	s_waitcnt lgkmcnt(0)
	v_mfma_f32_16x16x32_bf16 v[10:13], v[124:127], v[4:7], v[34:37]
	global_load_dwordx4 v[124:127], v[200:201], off offset:-4032
	s_waitcnt vmcnt(20)
	ds_bpermute_b32 v128, v107, v128
	ds_bpermute_b32 v129, v107, v129
	ds_bpermute_b32 v130, v107, v130
	ds_bpermute_b32 v131, v107, v131
	s_waitcnt lgkmcnt(0)
	v_mfma_f32_16x16x32_bf16 v[10:13], v[128:131], v[0:3], v[10:13]
	global_load_dwordx4 v[128:131], v[200:201], off offset:-2048
	s_nop 7
	v_pk_mul_f32 v[30:31], v[12:13], s[6:7] op_sel_hi:[1,0]
	v_pk_mul_f32 v[36:37], v[10:11], s[6:7] op_sel_hi:[1,0]
	s_nop 0
	v_mov_b32_e32 v39, v38
	v_mov_b32_e32 v40, v38
	v_mov_b32_e32 v41, v38
	s_nop 0
	s_waitcnt vmcnt(20)
	ds_bpermute_b32 v132, v107, v132
	ds_bpermute_b32 v133, v107, v133
	ds_bpermute_b32 v134, v107, v134
	ds_bpermute_b32 v135, v107, v135
	s_waitcnt lgkmcnt(0)
	v_mfma_f32_16x16x32_bf16 v[10:13], v[132:135], v[4:7], v[38:41]
	global_load_dwordx4 v[132:135], v[200:201], off offset:-1984
	s_waitcnt vmcnt(20)
	ds_bpermute_b32 v136, v107, v136
	ds_bpermute_b32 v137, v107, v137
	ds_bpermute_b32 v138, v107, v138
	ds_bpermute_b32 v139, v107, v139
	s_waitcnt lgkmcnt(0)
	v_mfma_f32_16x16x32_bf16 v[10:13], v[136:139], v[0:3], v[10:13]
	global_load_dwordx4 v[136:139], v[200:201], off
	s_nop 7
	v_pk_mul_f32 v[32:33], v[12:13], s[6:7] op_sel_hi:[1,0]
	v_pk_mul_f32 v[38:39], v[10:11], s[6:7] op_sel_hi:[1,0]
	s_nop 0
	v_mov_b32_e32 v45, v44
	v_mov_b32_e32 v46, v44
	v_mov_b32_e32 v47, v44
	s_nop 0
	s_waitcnt vmcnt(20)
	ds_bpermute_b32 v140, v107, v140
	ds_bpermute_b32 v141, v107, v141
	ds_bpermute_b32 v142, v107, v142
	ds_bpermute_b32 v143, v107, v143
	s_waitcnt lgkmcnt(0)
	v_mfma_f32_16x16x32_bf16 v[10:13], v[140:143], v[4:7], v[44:47]
	global_load_dwordx4 v[140:143], v[200:201], off offset:64
	s_waitcnt vmcnt(20)
	ds_bpermute_b32 v148, v107, v148
	ds_bpermute_b32 v149, v107, v149
	ds_bpermute_b32 v150, v107, v150
	ds_bpermute_b32 v151, v107, v151
	s_waitcnt lgkmcnt(0)
	v_mfma_f32_16x16x32_bf16 v[10:13], v[148:151], v[0:3], v[10:13]
	global_load_dwordx4 v[148:151], v[200:201], off offset:2048
	s_nop 7
	v_pk_mul_f32 v[34:35], v[12:13], s[6:7] op_sel_hi:[1,0]
	v_pk_mul_f32 v[42:43], v[10:11], s[6:7] op_sel_hi:[1,0]
	v_mov_b32_e32 v48, v145
	s_nop 0
	v_mov_b32_e32 v49, v48
	v_mov_b32_e32 v50, v48
	v_mov_b32_e32 v51, v48
	s_nop 0
	s_waitcnt vmcnt(20)
	ds_bpermute_b32 v152, v107, v152
	ds_bpermute_b32 v153, v107, v153
	ds_bpermute_b32 v154, v107, v154
	ds_bpermute_b32 v155, v107, v155
	s_waitcnt lgkmcnt(0)
	v_mfma_f32_16x16x32_bf16 v[10:13], v[152:155], v[4:7], v[48:51]
	global_load_dwordx4 v[152:155], v[200:201], off offset:2112
	s_nop 2
	v_mov_b32_e32 v50, v145
	s_waitcnt vmcnt(20)
	ds_bpermute_b32 v156, v107, v156
	ds_bpermute_b32 v157, v107, v157
	ds_bpermute_b32 v158, v107, v158
	ds_bpermute_b32 v159, v107, v159
	s_waitcnt lgkmcnt(0)
	v_mfma_f32_16x16x32_bf16 v[10:13], v[156:159], v[0:3], v[10:13]
	s_nop 7
	v_pk_mul_f32 v[44:45], v[10:11], s[6:7] op_sel_hi:[1,0]
	v_add_co_u32_e32 v10, vcc, s0, v8
	v_pk_mul_f32 v[40:41], v[12:13], s[6:7] op_sel_hi:[1,0]
	s_nop 0
	v_addc_co_u32_e32 v11, vcc, 0, v9, vcc
	s_movk_i32 s0, 0x6000
	v_mov_b32_e32 v51, v50
	v_mov_b32_e32 v52, v50
	v_mov_b32_e32 v53, v50
	s_nop 0
	s_waitcnt vmcnt(19)
	ds_bpermute_b32 v160, v107, v160
	ds_bpermute_b32 v161, v107, v161
	ds_bpermute_b32 v162, v107, v162
	ds_bpermute_b32 v163, v107, v163
	s_waitcnt lgkmcnt(0)
	v_mfma_f32_16x16x32_bf16 v[12:15], v[160:163], v[4:7], v[50:53]
	s_waitcnt vmcnt(18)
	ds_bpermute_b32 v164, v107, v164
	ds_bpermute_b32 v165, v107, v165
	ds_bpermute_b32 v166, v107, v166
	ds_bpermute_b32 v167, v107, v167
	s_waitcnt lgkmcnt(0)
	v_mfma_f32_16x16x32_bf16 v[12:15], v[164:167], v[0:3], v[12:15]
	s_nop 7
	v_pk_mul_f32 v[46:47], v[14:15], s[6:7] op_sel_hi:[1,0]
	v_pk_mul_f32 v[50:51], v[12:13], s[6:7] op_sel_hi:[1,0]
	s_nop 0
	s_nop 0
	v_mov_b32_e32 v57, v56
	v_mov_b32_e32 v58, v56
	v_mov_b32_e32 v59, v56
	s_nop 0
	s_waitcnt vmcnt(17)
	ds_bpermute_b32 v168, v107, v168
	ds_bpermute_b32 v169, v107, v169
	ds_bpermute_b32 v170, v107, v170
	ds_bpermute_b32 v171, v107, v171
	s_waitcnt lgkmcnt(0)
	v_mfma_f32_16x16x32_bf16 v[12:15], v[168:171], v[4:7], v[56:59]
	s_nop 2
	v_mov_b32_e32 v58, v145
	s_waitcnt vmcnt(16)
	ds_bpermute_b32 v172, v107, v172
	ds_bpermute_b32 v173, v107, v173
	ds_bpermute_b32 v174, v107, v174
	ds_bpermute_b32 v175, v107, v175
	s_waitcnt lgkmcnt(0)
	v_mfma_f32_16x16x32_bf16 v[12:15], v[172:175], v[0:3], v[12:15]
	s_nop 7
	v_pk_mul_f32 v[48:49], v[14:15], s[6:7] op_sel_hi:[1,0]
	v_pk_mul_f32 v[52:53], v[12:13], s[6:7] op_sel_hi:[1,0]
	s_nop 0
	v_mov_b32_e32 v59, v58
	v_mov_b32_e32 v60, v58
	v_mov_b32_e32 v61, v58
	s_nop 0
	s_waitcnt vmcnt(15)
; __device__ __forceinline__ float ozero() { float z = 0.f; asm volatile("" : "+v"(z)); return z; }
; __device__ __forceinline__ f32x4 mfma16(bf16x8 a, bf16x8 b, f32x4 c) { return __builtin_amdgcn_mfma_f32_16x16x32_bf16(a, b, c, 0, 0, 0); }
; __device__ __forceinline__ void mem_attn(const Params& p, int layer, int task) {
;     ...
; #pragma unroll
;   for (int kb = 0; kb < 16; kb++) {
;     const bf* kp = mk + (size_t)(16 * kb + n16) * 64 + 8 * kq;
;     bf16x8 a0 = *(const bf16x8*)kp, a1 = *(const bf16x8*)(kp + 32);
;     const float z_ = ozero(); f32x4 acc = {z_, z_, z_, z_};
;     acc = mfma16(a0, qf[0], acc); acc = mfma16(a1, qf[1], acc);
;     st[kb] = acc * 0.125f;
;   }
	ds_bpermute_b32 v176, v107, v176
	ds_bpermute_b32 v177, v107, v177
	ds_bpermute_b32 v178, v107, v178
	ds_bpermute_b32 v179, v107, v179
	s_waitcnt lgkmcnt(0)
	v_mfma_f32_16x16x32_bf16 v[12:15], v[176:179], v[4:7], v[58:61]
	s_waitcnt vmcnt(14)
	ds_bpermute_b32 v180, v107, v180
	ds_bpermute_b32 v181, v107, v181
	ds_bpermute_b32 v182, v107, v182
	ds_bpermute_b32 v183, v107, v183
	s_waitcnt lgkmcnt(0)
	v_mfma_f32_16x16x32_bf16 v[12:15], v[180:183], v[0:3], v[12:15]
	s_nop 7
	v_pk_mul_f32 v[54:55], v[14:15], s[6:7] op_sel_hi:[1,0]
	v_pk_mul_f32 v[58:59], v[12:13], s[6:7] op_sel_hi:[1,0]
	s_nop 0
	v_mov_b32_e32 v65, v64
	v_mov_b32_e32 v66, v64
	v_mov_b32_e32 v67, v64
	s_nop 0
	s_waitcnt vmcnt(13)
	ds_bpermute_b32 v184, v107, v184
	ds_bpermute_b32 v185, v107, v185
	ds_bpermute_b32 v186, v107, v186
	ds_bpermute_b32 v187, v107, v187
	s_waitcnt lgkmcnt(0)
	v_mfma_f32_16x16x32_bf16 v[10:13], v[184:187], v[4:7], v[64:67]
	v_add_co_u32_e32 v14, vcc, s43, v8
	s_nop 1
	v_mov_b32_e32 v66, v145
	s_waitcnt vmcnt(12)
	ds_bpermute_b32 v188, v107, v188
	ds_bpermute_b32 v189, v107, v189
	ds_bpermute_b32 v190, v107, v190
	ds_bpermute_b32 v191, v107, v191
	s_waitcnt lgkmcnt(0)
	v_mfma_f32_16x16x32_bf16 v[10:13], v[188:191], v[0:3], v[10:13]
	v_addc_co_u32_e32 v15, vcc, 0, v9, vcc
	v_add_co_u32_e32 v78, vcc, s0, v8
	s_mov_b32 s0, 0xff61b1e6
	s_nop 0
	v_addc_co_u32_e32 v79, vcc, 0, v9, vcc
	s_nop 2
	v_pk_mul_f32 v[56:57], v[12:13], s[6:7] op_sel_hi:[1,0]
	v_pk_mul_f32 v[60:61], v[10:11], s[6:7] op_sel_hi:[1,0]
	v_add_co_u32_e32 v84, vcc, s47, v8
	v_mov_b32_e32 v67, v66
	v_mov_b32_e32 v68, v66
	v_mov_b32_e32 v69, v66
	v_addc_co_u32_e32 v85, vcc, 0, v9, vcc
	s_waitcnt vmcnt(11)
	ds_bpermute_b32 v192, v107, v192
	ds_bpermute_b32 v193, v107, v193
	ds_bpermute_b32 v194, v107, v194
	ds_bpermute_b32 v195, v107, v195
	s_waitcnt lgkmcnt(0)
	v_mfma_f32_16x16x32_bf16 v[10:13], v[192:195], v[4:7], v[66:69]
	s_waitcnt vmcnt(10)
	ds_bpermute_b32 v108, v107, v108
	ds_bpermute_b32 v109, v107, v109
	ds_bpermute_b32 v110, v107, v110
	ds_bpermute_b32 v111, v107, v111
	s_waitcnt lgkmcnt(0)
	v_mfma_f32_16x16x32_bf16 v[10:13], v[108:111], v[0:3], v[10:13]
	s_nop 7
	v_pk_mul_f32 v[62:63], v[12:13], s[6:7] op_sel_hi:[1,0]
	v_pk_mul_f32 v[66:67], v[10:11], s[6:7] op_sel_hi:[1,0]
	s_nop 0
	v_mov_b32_e32 v73, v72
	v_mov_b32_e32 v74, v72
	v_mov_b32_e32 v75, v72
	s_nop 0
	s_waitcnt vmcnt(9)
	ds_bpermute_b32 v112, v107, v112
	ds_bpermute_b32 v113, v107, v113
	ds_bpermute_b32 v114, v107, v114
	ds_bpermute_b32 v115, v107, v115
	s_waitcnt lgkmcnt(0)
	v_mfma_f32_16x16x32_bf16 v[10:13], v[112:115], v[4:7], v[72:75]
	s_nop 2
	v_mov_b32_e32 v74, v145
	s_waitcnt vmcnt(8)
	ds_bpermute_b32 v116, v107, v116
	ds_bpermute_b32 v117, v107, v117
	ds_bpermute_b32 v118, v107, v118
	ds_bpermute_b32 v119, v107, v119
	s_waitcnt lgkmcnt(0)
	v_mfma_f32_16x16x32_bf16 v[10:13], v[116:119], v[0:3], v[10:13]
	s_nop 7
	v_pk_mul_f32 v[64:65], v[12:13], s[6:7] op_sel_hi:[1,0]
	v_pk_mul_f32 v[68:69], v[10:11], s[6:7] op_sel_hi:[1,0]
	s_nop 0
	v_mov_b32_e32 v75, v74
	v_mov_b32_e32 v76, v74
	v_mov_b32_e32 v77, v74
	s_nop 0
	s_waitcnt vmcnt(7)
	ds_bpermute_b32 v120, v107, v120
	ds_bpermute_b32 v121, v107, v121
	ds_bpermute_b32 v122, v107, v122
	ds_bpermute_b32 v123, v107, v123
	s_waitcnt lgkmcnt(0)
	v_mfma_f32_16x16x32_bf16 v[10:13], v[120:123], v[4:7], v[74:77]
	s_waitcnt vmcnt(6)
	ds_bpermute_b32 v124, v107, v124
	ds_bpermute_b32 v125, v107, v125
	ds_bpermute_b32 v126, v107, v126
	ds_bpermute_b32 v127, v107, v127
	s_waitcnt lgkmcnt(0)
	v_mfma_f32_16x16x32_bf16 v[10:13], v[124:127], v[0:3], v[10:13]
	s_nop 7
	v_pk_mul_f32 v[70:71], v[12:13], s[6:7] op_sel_hi:[1,0]
	v_pk_mul_f32 v[72:73], v[10:11], s[6:7] op_sel_hi:[1,0]
	v_mov_b32_e32 v78, v145
	s_nop 0
	v_mov_b32_e32 v79, v78
	v_mov_b32_e32 v80, v78
	v_mov_b32_e32 v81, v78
	s_nop 0
	s_waitcnt vmcnt(5)
	ds_bpermute_b32 v128, v107, v128
	ds_bpermute_b32 v129, v107, v129
	ds_bpermute_b32 v130, v107, v130
	ds_bpermute_b32 v131, v107, v131
	s_waitcnt lgkmcnt(0)
	v_mfma_f32_16x16x32_bf16 v[10:13], v[128:131], v[4:7], v[78:81]
	s_nop 2
	v_mov_b32_e32 v78, v145
	s_waitcnt vmcnt(4)
	ds_bpermute_b32 v132, v107, v132
	ds_bpermute_b32 v133, v107, v133
	ds_bpermute_b32 v134, v107, v134
	ds_bpermute_b32 v135, v107, v135
	s_waitcnt lgkmcnt(0)
	v_mfma_f32_16x16x32_bf16 v[10:13], v[132:135], v[0:3], v[10:13]
	s_nop 7
	v_pk_mul_f32 v[74:75], v[12:13], s[6:7] op_sel_hi:[1,0]
	v_pk_mul_f32 v[76:77], v[10:11], s[6:7] op_sel_hi:[1,0]
	s_nop 0
	v_mov_b32_e32 v79, v78
	v_mov_b32_e32 v80, v78
	v_mov_b32_e32 v81, v78
	s_nop 0
	s_waitcnt vmcnt(3)
	ds_bpermute_b32 v136, v107, v136
	ds_bpermute_b32 v137, v107, v137
	ds_bpermute_b32 v138, v107, v138
	ds_bpermute_b32 v139, v107, v139
	s_waitcnt lgkmcnt(0)
	v_mfma_f32_16x16x32_bf16 v[8:11], v[136:139], v[4:7], v[78:81]
	s_waitcnt vmcnt(2)
	ds_bpermute_b32 v140, v107, v140
	ds_bpermute_b32 v141, v107, v141
	ds_bpermute_b32 v142, v107, v142
	ds_bpermute_b32 v143, v107, v143
	s_waitcnt lgkmcnt(0)
	v_mfma_f32_16x16x32_bf16 v[8:11], v[140:143], v[0:3], v[8:11]
	s_nop 7
	v_pk_mul_f32 v[78:79], v[10:11], s[6:7] op_sel_hi:[1,0]
	v_pk_mul_f32 v[80:81], v[8:9], s[6:7] op_sel_hi:[1,0]
	v_mov_b32_e32 v84, v145
	s_nop 0
	v_mov_b32_e32 v85, v84
	v_mov_b32_e32 v86, v84
	v_mov_b32_e32 v87, v84
	s_nop 0
	s_waitcnt vmcnt(1)
	ds_bpermute_b32 v148, v107, v148
	ds_bpermute_b32 v149, v107, v149
	ds_bpermute_b32 v150, v107, v150
	ds_bpermute_b32 v151, v107, v151
	s_waitcnt lgkmcnt(0)
	v_mfma_f32_16x16x32_bf16 v[4:7], v[148:151], v[4:7], v[84:87]
	s_waitcnt vmcnt(0)
	ds_bpermute_b32 v152, v107, v152
	ds_bpermute_b32 v153, v107, v153
	ds_bpermute_b32 v154, v107, v154
	ds_bpermute_b32 v155, v107, v155
	s_waitcnt lgkmcnt(0)
; __device__ __forceinline__ void mem_attn(const Params& p, int layer, int task) {
;     ...
;   float mx = -3.0e38f;
; #pragma unroll
;   for (int kb = 0; kb < 16; kb++)
; #pragma unroll
;     for (int r = 0; r < 4; r++) mx = fmaxf(mx, st[kb][r]);
;   mx = fmaxf(mx, __shfl_xor(mx, 16)); mx = fmaxf(mx, __shfl_xor(mx, 32));
;   float sum = 0.f;
; #pragma unroll
;   for (int kb = 0; kb < 16; kb++)
; #pragma unroll
;     for (int r = 0; r < 4; r++) { float e = __expf(st[kb][r] - mx); st[kb][r] = e; sum += e; }
	v_mfma_f32_16x16x32_bf16 v[2:5], v[152:155], v[0:3], v[4:7]
	s_nop 5
	v_and_b32_e32 v6, 64, v202
	v_add_u32_e32 v7, 64, v6
	v_pk_mul_f32 v[0:1], v[4:5], s[6:7] op_sel_hi:[1,0]
	v_max3_f32 v4, v26, s0, v27
	v_max3_f32 v4, v4, v22, v23
	v_max3_f32 v4, v4, v28, v29
	v_max3_f32 v4, v4, v24, v25
	v_max3_f32 v4, v4, v36, v37
	v_max3_f32 v4, v4, v30, v31
	v_max3_f32 v4, v4, v38, v39
	v_max3_f32 v4, v4, v32, v33
	v_max3_f32 v4, v4, v42, v43
	v_max3_f32 v4, v4, v34, v35
	v_max3_f32 v4, v4, v44, v45
	v_max3_f32 v4, v4, v40, v41
	v_max3_f32 v4, v4, v50, v51
	v_max3_f32 v4, v4, v46, v47
	v_max3_f32 v4, v4, v52, v53
	v_max3_f32 v4, v4, v48, v49
	v_max3_f32 v4, v4, v58, v59
	v_max3_f32 v4, v4, v54, v55
	v_max3_f32 v4, v4, v60, v61
	v_max3_f32 v4, v4, v56, v57
	v_max3_f32 v4, v4, v66, v67
	v_max3_f32 v4, v4, v62, v63
	v_max3_f32 v4, v4, v68, v69
	v_max3_f32 v4, v4, v64, v65
	v_max3_f32 v4, v4, v72, v73
	v_max3_f32 v4, v4, v70, v71
	v_max3_f32 v4, v4, v76, v77
	v_max3_f32 v4, v4, v74, v75
	v_max3_f32 v4, v4, v80, v81
	v_xor_b32_e32 v5, 16, v202
	v_pk_mul_f32 v[2:3], v[2:3], s[6:7] op_sel_hi:[1,0]
	v_max3_f32 v4, v4, v78, v79
	v_cmp_lt_i32_e32 vcc, v5, v7
	v_max3_f32 v4, v4, v2, v3
	v_max3_f32 v4, v4, v0, v1
	v_cndmask_b32_e32 v5, v202, v5, vcc
	v_lshlrev_b32_e32 v6, 2, v5
	ds_bpermute_b32 v5, v6, v4
	s_mov_b64 s[0:1], 0xc0
	s_waitcnt lgkmcnt(0)
	v_max_f32_e32 v5, v5, v5
	v_max_f32_e32 v4, v4, v5
	v_xor_b32_e32 v5, 32, v202
	v_cmp_lt_i32_e32 vcc, v5, v7
	s_nop 1
	v_cndmask_b32_e32 v5, v202, v5, vcc
	v_lshlrev_b32_e32 v7, 2, v5
	ds_bpermute_b32 v5, v7, v4
	s_waitcnt lgkmcnt(0)
	v_max_f32_e32 v5, v5, v5
	v_max_f32_e32 v15, v4, v5
	v_sub_f32_e32 v9, v22, v15
	v_mul_f32_e32 v9, 0x3fb8aa3b, v9
	v_exp_f32_e32 v93, v9
	v_sub_f32_e32 v9, v23, v15
	v_mul_f32_e32 v9, 0x3fb8aa3b, v9
	v_exp_f32_e32 v95, v9
	v_sub_f32_e32 v9, v28, v15
	v_mul_f32_e32 v9, 0x3fb8aa3b, v9
	v_exp_f32_e32 v96, v9
	v_sub_f32_e32 v9, v29, v15
	v_mul_f32_e32 v9, 0x3fb8aa3b, v9
	v_exp_f32_e32 v99, v9
	v_sub_f32_e32 v9, v24, v15
	v_mul_f32_e32 v9, 0x3fb8aa3b, v9
	v_exp_f32_e32 v101, v9
	v_sub_f32_e32 v9, v25, v15
	v_mul_f32_e32 v9, 0x3fb8aa3b, v9
	v_exp_f32_e32 v103, v9
	v_sub_f32_e32 v9, v36, v15
	v_mul_f32_e32 v9, 0x3fb8aa3b, v9
	v_exp_f32_e32 v94, v9
	v_sub_f32_e32 v9, v37, v15
	v_mul_f32_e32 v9, 0x3fb8aa3b, v9
	v_exp_f32_e32 v97, v9
	v_sub_f32_e32 v9, v30, v15
	v_mul_f32_e32 v9, 0x3fb8aa3b, v9
	v_exp_f32_e32 v98, v9
	v_sub_f32_e32 v9, v31, v15
	v_mul_f32_e32 v9, 0x3fb8aa3b, v9
	v_exp_f32_e32 v100, v9
	v_sub_f32_e32 v9, v38, v15
	v_mul_f32_e32 v9, 0x3fb8aa3b, v9
	v_exp_f32_e32 v102, v9
	v_sub_f32_e32 v9, v39, v15
	v_mul_f32_e32 v9, 0x3fb8aa3b, v9
	v_exp_f32_e32 v104, v9
	v_sub_f32_e32 v9, v32, v15
	v_mul_f32_e32 v9, 0x3fb8aa3b, v9
	v_exp_f32_e32 v105, v9
	v_sub_f32_e32 v9, v33, v15
	v_mul_f32_e32 v9, 0x3fb8aa3b, v9
	v_exp_f32_e32 v106, v9
	v_sub_f32_e32 v9, v42, v15
	v_mul_f32_e32 v9, 0x3fb8aa3b, v9
	v_exp_f32_e32 v85, v9
	v_sub_f32_e32 v9, v43, v15
	v_mul_f32_e32 v9, 0x3fb8aa3b, v9
	v_exp_f32_e32 v86, v9
	v_sub_f32_e32 v9, v34, v15
	v_mul_f32_e32 v9, 0x3fb8aa3b, v9
	v_exp_f32_e32 v87, v9
	v_sub_f32_e32 v9, v35, v15
	v_mul_f32_e32 v9, 0x3fb8aa3b, v9
	v_exp_f32_e32 v88, v9
	v_sub_f32_e32 v9, v44, v15
	v_mul_f32_e32 v9, 0x3fb8aa3b, v9
	v_exp_f32_e32 v89, v9
	v_sub_f32_e32 v9, v45, v15
	v_mul_f32_e32 v9, 0x3fb8aa3b, v9
	v_exp_f32_e32 v90, v9
	v_sub_f32_e32 v9, v40, v15
	v_mul_f32_e32 v9, 0x3fb8aa3b, v9
	v_exp_f32_e32 v91, v9
	v_sub_f32_e32 v9, v41, v15
	v_mul_f32_e32 v9, 0x3fb8aa3b, v9
	v_exp_f32_e32 v92, v9
	v_sub_f32_e32 v9, v50, v15
	v_mul_f32_e32 v9, 0x3fb8aa3b, v9
	v_exp_f32_e32 v50, v9
	v_sub_f32_e32 v9, v51, v15
	v_mul_f32_e32 v9, 0x3fb8aa3b, v9
	v_exp_f32_e32 v51, v9
	v_sub_f32_e32 v9, v46, v15
	v_mul_f32_e32 v9, 0x3fb8aa3b, v9
	v_exp_f32_e32 v84, v9
	v_sub_f32_e32 v9, v47, v15
	v_sub_f32_e32 v4, v26, v15
	v_mul_f32_e32 v9, 0x3fb8aa3b, v9
	v_mul_f32_e32 v4, 0x3fb8aa3b, v4
	v_sub_f32_e32 v5, v27, v15
	v_exp_f32_e32 v47, v9
	v_sub_f32_e32 v9, v52, v15
	v_exp_f32_e32 v4, v4
	v_mul_f32_e32 v5, 0x3fb8aa3b, v5
	v_mul_f32_e32 v9, 0x3fb8aa3b, v9
	v_exp_f32_e32 v5, v5
	v_exp_f32_e32 v52, v9
	v_sub_f32_e32 v9, v53, v15
	v_mul_f32_e32 v9, 0x3fb8aa3b, v9
	v_exp_f32_e32 v53, v9
	v_sub_f32_e32 v9, v48, v15
	v_add_f32_e32 v8, 0, v4
	v_mul_f32_e32 v9, 0x3fb8aa3b, v9
	v_add_f32_e32 v8, v5, v8
	v_exp_f32_e32 v48, v9
	v_sub_f32_e32 v9, v49, v15
	v_add_f32_e32 v8, v93, v8
	v_mul_f32_e32 v9, 0x3fb8aa3b, v9
	v_add_f32_e32 v8, v95, v8
	v_exp_f32_e32 v49, v9
	v_sub_f32_e32 v9, v58, v15
	v_add_f32_e32 v8, v96, v8
	v_mul_f32_e32 v9, 0x3fb8aa3b, v9
	v_add_f32_e32 v8, v99, v8
	v_exp_f32_e32 v39, v9
	v_sub_f32_e32 v9, v59, v15
	v_add_f32_e32 v8, v101, v8
	v_mul_f32_e32 v9, 0x3fb8aa3b, v9
	v_add_f32_e32 v8, v103, v8
	v_exp_f32_e32 v40, v9
	v_sub_f32_e32 v9, v54, v15
	v_add_f32_e32 v8, v94, v8
	v_mul_f32_e32 v9, 0x3fb8aa3b, v9
	v_add_f32_e32 v8, v97, v8
	v_exp_f32_e32 v41, v9
	v_sub_f32_e32 v9, v55, v15
	v_add_f32_e32 v8, v98, v8
	v_mul_f32_e32 v9, 0x3fb8aa3b, v9
	v_add_f32_e32 v8, v100, v8
	v_exp_f32_e32 v42, v9
	v_sub_f32_e32 v9, v60, v15
	v_add_f32_e32 v8, v102, v8
	v_mul_f32_e32 v9, 0x3fb8aa3b, v9
	v_add_f32_e32 v8, v104, v8
	v_exp_f32_e32 v43, v9
	v_sub_f32_e32 v9, v61, v15
	v_add_f32_e32 v8, v105, v8
	v_mul_f32_e32 v9, 0x3fb8aa3b, v9
	v_add_f32_e32 v8, v106, v8
	v_exp_f32_e32 v44, v9
	v_sub_f32_e32 v9, v56, v15
	v_add_f32_e32 v8, v85, v8
	v_mul_f32_e32 v9, 0x3fb8aa3b, v9
	v_add_f32_e32 v8, v86, v8
	v_exp_f32_e32 v45, v9
	v_sub_f32_e32 v9, v57, v15
	v_add_f32_e32 v8, v87, v8
	v_mul_f32_e32 v9, 0x3fb8aa3b, v9
	v_add_f32_e32 v8, v88, v8
	v_exp_f32_e32 v46, v9
	v_sub_f32_e32 v9, v66, v15
	v_add_f32_e32 v8, v89, v8
; __device__ __forceinline__ float ozero() { float z = 0.f; asm volatile("" : "+v"(z)); return z; }
; __device__ __forceinline__ void mem_attn(const Params& p, int layer, int task) {
;     ...
;   float sum = 0.f;
; #pragma unroll
;   for (int kb = 0; kb < 16; kb++)
; #pragma unroll
;     for (int r = 0; r < 4; r++) { float e = __expf(st[kb][r] - mx); st[kb][r] = e; sum += e; }
;   sum += __shfl_xor(sum, 16); sum += __shfl_xor(sum, 32);
;   const float rinv = 1.f / sum;
;   f32x4 o[4];
; #pragma unroll
;   for (int mb = 0; mb < 4; mb++) { const float z_ = ozero(); o[mb] = (f32x4){z_, z_, z_, z_}; }
; #pragma unroll
;   for (int k2 = 0; k2 < 8; k2++) {
;     bf16x8 pf;
;     unsigned q0 = pk2(st[2 * k2][0], st[2 * k2][1]), q1 = pk2(st[2 * k2][2], st[2 * k2][3]);
;     unsigned q2 = pk2(st[2 * k2 + 1][0], st[2 * k2 + 1][1]), q3 = pk2(st[2 * k2 + 1][2], st[2 * k2 + 1][3]);
;     pf[0] = (short)(q0 & 0xFFFF); pf[1] = (short)(q0 >> 16); pf[2] = (short)(q1 & 0xFFFF); pf[3] = (short)(q1 >> 16);
;     pf[4] = (short)(q2 & 0xFFFF); pf[5] = (short)(q2 >> 16); pf[6] = (short)(q3 & 0xFFFF); pf[7] = (short)(q3 >> 16);
; #pragma unroll
;     for (int mb = 0; mb < 4; mb++) {
;       const bf* vp = mvt + (size_t)(16 * mb + n16) * 256 + 32 * k2 + 4 * kq;
;       uint2 v0 = *(const uint2*)vp, v1 = *(const uint2*)(vp + 16);
	v_mul_f32_e32 v9, 0x3fb8aa3b, v9
	v_add_f32_e32 v8, v90, v8
	v_exp_f32_e32 v31, v9
	v_sub_f32_e32 v9, v67, v15
	v_add_f32_e32 v8, v91, v8
	v_mul_f32_e32 v9, 0x3fb8aa3b, v9
	v_add_f32_e32 v8, v92, v8
	v_exp_f32_e32 v32, v9
	v_sub_f32_e32 v9, v62, v15
	v_add_f32_e32 v8, v50, v8
	v_mul_f32_e32 v9, 0x3fb8aa3b, v9
	v_add_f32_e32 v8, v51, v8
	v_exp_f32_e32 v33, v9
	v_sub_f32_e32 v9, v63, v15
	v_add_f32_e32 v8, v84, v8
	v_mul_f32_e32 v9, 0x3fb8aa3b, v9
	v_add_f32_e32 v8, v47, v8
	v_exp_f32_e32 v34, v9
	v_sub_f32_e32 v9, v68, v15
	v_add_f32_e32 v8, v52, v8
	v_mul_f32_e32 v9, 0x3fb8aa3b, v9
	v_add_f32_e32 v8, v53, v8
	v_exp_f32_e32 v35, v9
	v_sub_f32_e32 v9, v69, v15
	v_add_f32_e32 v8, v48, v8
	v_mul_f32_e32 v9, 0x3fb8aa3b, v9
	v_add_f32_e32 v8, v49, v8
	v_exp_f32_e32 v36, v9
	v_sub_f32_e32 v9, v64, v15
	v_add_f32_e32 v8, v39, v8
	v_mul_f32_e32 v9, 0x3fb8aa3b, v9
	v_add_f32_e32 v8, v40, v8
	v_exp_f32_e32 v37, v9
	v_sub_f32_e32 v9, v65, v15
	v_add_f32_e32 v8, v41, v8
	v_mul_f32_e32 v9, 0x3fb8aa3b, v9
	v_add_f32_e32 v8, v42, v8
	v_exp_f32_e32 v38, v9
	v_sub_f32_e32 v9, v72, v15
	v_add_f32_e32 v8, v43, v8
	v_mul_f32_e32 v9, 0x3fb8aa3b, v9
	v_add_f32_e32 v8, v44, v8
	v_exp_f32_e32 v23, v9
	v_sub_f32_e32 v9, v73, v15
	v_add_f32_e32 v8, v45, v8
	v_mul_f32_e32 v9, 0x3fb8aa3b, v9
	v_add_f32_e32 v8, v46, v8
	v_exp_f32_e32 v24, v9
	v_sub_f32_e32 v9, v70, v15
	v_add_f32_e32 v8, v31, v8
	v_mul_f32_e32 v9, 0x3fb8aa3b, v9
	v_add_f32_e32 v8, v32, v8
	v_exp_f32_e32 v25, v9
	v_sub_f32_e32 v9, v71, v15
	v_add_f32_e32 v8, v33, v8
	v_mul_f32_e32 v9, 0x3fb8aa3b, v9
	v_add_f32_e32 v8, v34, v8
	v_exp_f32_e32 v26, v9
	v_sub_f32_e32 v9, v76, v15
	v_add_f32_e32 v8, v35, v8
	v_mul_f32_e32 v9, 0x3fb8aa3b, v9
	v_add_f32_e32 v8, v36, v8
	v_exp_f32_e32 v27, v9
	v_sub_f32_e32 v9, v77, v15
	v_add_f32_e32 v8, v37, v8
	v_mul_f32_e32 v9, 0x3fb8aa3b, v9
	v_add_f32_e32 v8, v38, v8
	v_exp_f32_e32 v28, v9
	v_sub_f32_e32 v9, v74, v15
	v_add_f32_e32 v8, v23, v8
	v_mul_f32_e32 v9, 0x3fb8aa3b, v9
	v_add_f32_e32 v8, v24, v8
	v_exp_f32_e32 v29, v9
	v_sub_f32_e32 v9, v75, v15
	v_add_f32_e32 v8, v25, v8
	v_mul_f32_e32 v9, 0x3fb8aa3b, v9
	v_add_f32_e32 v8, v26, v8
	v_exp_f32_e32 v30, v9
	v_add_f32_e32 v8, v27, v8
	v_add_f32_e32 v8, v28, v8
	v_add_f32_e32 v8, v29, v8
	v_add_f32_e32 v9, v30, v8
	v_sub_f32_e32 v8, v80, v15
	v_mul_f32_e32 v8, 0x3fb8aa3b, v8
	v_exp_f32_e32 v8, v8
	v_sub_f32_e32 v2, v2, v15
	v_mul_f32_e32 v2, 0x3fb8aa3b, v2
	v_sub_f32_e32 v3, v3, v15
	v_add_f32_e32 v10, v8, v9
	v_sub_f32_e32 v9, v81, v15
	v_mul_f32_e32 v9, 0x3fb8aa3b, v9
	v_exp_f32_e32 v9, v9
	v_mul_f32_e32 v3, 0x3fb8aa3b, v3
	v_sub_f32_e32 v0, v0, v15
	v_mul_f32_e32 v0, 0x3fb8aa3b, v0
	v_add_f32_e32 v11, v9, v10
	v_sub_f32_e32 v10, v78, v15
	v_mul_f32_e32 v10, 0x3fb8aa3b, v10
	v_exp_f32_e32 v10, v10
	v_sub_f32_e32 v1, v1, v15
	v_exp_f32_e32 v14, v0
	v_mul_f32_e32 v1, 0x3fb8aa3b, v1
	v_add_f32_e32 v12, v10, v11
	v_sub_f32_e32 v11, v79, v15
	v_mul_f32_e32 v11, 0x3fb8aa3b, v11
	v_exp_f32_e32 v11, v11
	v_exp_f32_e32 v15, v1
	v_mov_b32_e32 v54, v145
	v_mov_b32_e32 v58, v145
	v_add_f32_e32 v13, v11, v12
	v_exp_f32_e32 v12, v2
	v_mov_b32_e32 v62, v145
	v_mov_b32_e32 v66, v145
	v_add_f32_e32 v2, v12, v13
	v_exp_f32_e32 v13, v3
	v_cvt_pk_bf16_f32 v70, v4, v5
	v_add_f32_e32 v2, v13, v2
	v_add_f32_e32 v0, v14, v2
	v_add_f32_e32 v0, v15, v0
	ds_bpermute_b32 v1, v6, v0
	v_mov_b32_e32 v55, v54
	v_mov_b32_e32 v56, v54
	v_mov_b32_e32 v57, v54
	v_cvt_pk_bf16_f32 v71, v93, v95
	s_waitcnt lgkmcnt(0)
	v_add_f32_e32 v0, v0, v1
	ds_bpermute_b32 v1, v7, v0
	v_cvt_pk_bf16_f32 v72, v96, v99
	v_cvt_pk_bf16_f32 v73, v101, v103
	v_mov_b32_e32 v59, v58
	v_mov_b32_e32 v60, v58
	s_waitcnt lgkmcnt(0)
	v_add_f32_e32 v22, v0, v1
	v_lshl_add_u64 v[0:1], s[8:9], 0, v[144:145]
	v_lshl_add_u64 v[6:7], v[0:1], 0, v[18:19]
	v_lshlrev_b32_e32 v144, 9, v83
	v_lshl_add_u64 v[0:1], v[6:7], 0, v[144:145]
	v_and_b32_e32 v146, 15, v202
	v_lshrrev_b32_e32 v147, 4, v202
	v_lshlrev_b32_e32 v146, 9, v146
	v_lshl_add_u32 v146, v147, 3, v146
	v_lshrrev_b32_e32 v147, 2, v202
	v_lshlrev_b32_e32 v147, 9, v147
	v_sub_u32_e32 v146, v147, v146
	v_and_b32_e32 v147, 3, v202
	v_lshl_add_u32 v146, v147, 3, v146
	v_ashrrev_i32_e32 v147, 31, v146
	v_lshl_add_u64 v[200:201], v[0:1], 0, v[146:147]
	v_mov_b32_e32 v198, 0x2000
	v_mov_b32_e32 v199, 0
	v_lshl_add_u64 v[146:147], v[200:201], 0, v[198:199]
	v_lshl_add_u64 v[196:197], v[146:147], 0, v[198:199]
	v_lshl_add_u64 v[198:199], v[196:197], 0, v[198:199]
	global_load_dwordx2 v[108:109], v[200:201], off
	global_load_dwordx2 v[110:111], v[200:201], off offset:32
	global_load_dwordx2 v[112:113], v[146:147], off
	global_load_dwordx2 v[114:115], v[146:147], off offset:32
	global_load_dwordx2 v[116:117], v[196:197], off
	global_load_dwordx2 v[118:119], v[196:197], off offset:32
	global_load_dwordx2 v[120:121], v[198:199], off
	global_load_dwordx2 v[122:123], v[198:199], off offset:32
	global_load_dwordx2 v[124:125], v[200:201], off offset:64
	global_load_dwordx2 v[126:127], v[200:201], off offset:96
	global_load_dwordx2 v[128:129], v[146:147], off offset:64
	global_load_dwordx2 v[130:131], v[146:147], off offset:96
	global_load_dwordx2 v[132:133], v[196:197], off offset:64
	global_load_dwordx2 v[134:135], v[196:197], off offset:96
	global_load_dwordx2 v[136:137], v[198:199], off offset:64
	global_load_dwordx2 v[138:139], v[198:199], off offset:96
	global_load_dwordx2 v[140:141], v[200:201], off offset:128
	global_load_dwordx2 v[142:143], v[200:201], off offset:160
	global_load_dwordx2 v[148:149], v[146:147], off offset:128
	global_load_dwordx2 v[150:151], v[146:147], off offset:160
	global_load_dwordx2 v[152:153], v[196:197], off offset:128
; __device__ __forceinline__ f32x4 mfma16(bf16x8 a, bf16x8 b, f32x4 c) { return __builtin_amdgcn_mfma_f32_16x16x32_bf16(a, b, c, 0, 0, 0); }
; __device__ __forceinline__ void mem_attn(const Params& p, int layer, int task) {
;     ...
;   for (int k2 = 0; k2 < 8; k2++) {
;     bf16x8 pf;
;     unsigned q0 = pk2(st[2 * k2][0], st[2 * k2][1]), q1 = pk2(st[2 * k2][2], st[2 * k2][3]);
;     unsigned q2 = pk2(st[2 * k2 + 1][0], st[2 * k2 + 1][1]), q3 = pk2(st[2 * k2 + 1][2], st[2 * k2 + 1][3]);
;     pf[0] = (short)(q0 & 0xFFFF); pf[1] = (short)(q0 >> 16); pf[2] = (short)(q1 & 0xFFFF); pf[3] = (short)(q1 >> 16);
;     pf[4] = (short)(q2 & 0xFFFF); pf[5] = (short)(q2 >> 16); pf[6] = (short)(q3 & 0xFFFF); pf[7] = (short)(q3 >> 16);
; #pragma unroll
;     for (int mb = 0; mb < 4; mb++) {
;       const bf* vp = mvt + (size_t)(16 * mb + n16) * 256 + 32 * k2 + 4 * kq;
;       uint2 v0 = *(const uint2*)vp, v1 = *(const uint2*)(vp + 16);
;       bf16x8 af;
;       af[0] = (short)(v0.x & 0xFFFF); af[1] = (short)(v0.x >> 16); af[2] = (short)(v0.y & 0xFFFF); af[3] = (short)(v0.y >> 16);
;       af[4] = (short)(v1.x & 0xFFFF); af[5] = (short)(v1.x >> 16); af[6] = (short)(v1.y & 0xFFFF); af[7] = (short)(v1.y >> 16);
;       o[mb] = mfma16(af, pf, o[mb]);
;     }
	global_load_dwordx2 v[154:155], v[196:197], off offset:160
	global_load_dwordx2 v[156:157], v[198:199], off offset:128
	global_load_dwordx2 v[158:159], v[198:199], off offset:160
	global_load_dwordx2 v[160:161], v[200:201], off offset:192
	global_load_dwordx2 v[162:163], v[200:201], off offset:224
	global_load_dwordx2 v[164:165], v[146:147], off offset:192
	global_load_dwordx2 v[166:167], v[146:147], off offset:224
	global_load_dwordx2 v[168:169], v[196:197], off offset:192
	global_load_dwordx2 v[170:171], v[196:197], off offset:224
	global_load_dwordx2 v[172:173], v[198:199], off offset:192
	global_load_dwordx2 v[174:175], v[198:199], off offset:224
	global_load_dwordx2 v[176:177], v[200:201], off offset:256
	global_load_dwordx2 v[178:179], v[200:201], off offset:288
	global_load_dwordx2 v[180:181], v[146:147], off offset:256
	global_load_dwordx2 v[182:183], v[146:147], off offset:288
	global_load_dwordx2 v[184:185], v[196:197], off offset:256
	global_load_dwordx2 v[186:187], v[196:197], off offset:288
	global_load_dwordx2 v[188:189], v[198:199], off offset:256
	global_load_dwordx2 v[190:191], v[198:199], off offset:288
	global_load_dwordx2 v[192:193], v[200:201], off offset:320
	global_load_dwordx2 v[194:195], v[200:201], off offset:352
	v_mov_b32_e32 v61, v58
	v_mov_b32_e32 v63, v62
	v_mov_b32_e32 v64, v62
	v_mov_b32_e32 v65, v62
	v_mov_b32_e32 v67, v66
	v_mov_b32_e32 v68, v66
	v_mov_b32_e32 v69, v66
	v_lshl_add_u64 v[78:79], v[6:7], 0, 64
	v_cvt_pk_bf16_f32 v50, v50, v51
	v_cvt_pk_bf16_f32 v51, v84, v47
	v_cvt_pk_bf16_f32 v52, v52, v53
	v_cvt_pk_bf16_f32 v53, v48, v49
	v_lshl_add_u64 v[48:49], v[6:7], 0, s[0:1]
	v_cvt_pk_bf16_f32 v41, v41, v42
	v_cvt_pk_bf16_f32 v42, v43, v44
	v_cvt_pk_bf16_f32 v43, v45, v46
	v_cvt_pk_bf16_f32 v40, v39, v40
	v_cvt_pk_bf16_f32 v33, v33, v34
	v_cvt_pk_bf16_f32 v34, v35, v36
	v_cvt_pk_bf16_f32 v35, v37, v38
	s_mov_b64 s[0:1], 0x140
	v_cvt_pk_bf16_f32 v32, v31, v32
	v_cvt_pk_bf16_f32 v25, v25, v26
	v_cvt_pk_bf16_f32 v26, v27, v28
	v_cvt_pk_bf16_f32 v27, v29, v30
	v_cvt_pk_bf16_f32 v24, v23, v24
	s_nop 0
	s_nop 1
	s_waitcnt vmcnt(40)
	ds_bpermute_b32 v108, v107, v108
	ds_bpermute_b32 v109, v107, v109
	ds_bpermute_b32 v110, v107, v110
	ds_bpermute_b32 v111, v107, v111
	s_waitcnt lgkmcnt(0)
	v_mfma_f32_16x16x32_bf16 v[54:57], v[108:111], v[70:73], v[54:57]
	global_load_dwordx2 v[108:109], v[146:147], off offset:320
	global_load_dwordx2 v[110:111], v[146:147], off offset:352
	v_or_b32_e32 v2, 0x2000, v144
	v_mov_b32_e32 v3, v145
	v_lshl_add_u64 v[4:5], v[6:7], 0, v[2:3]
	v_or_b32_e32 v4, 0x4000, v144
	v_mov_b32_e32 v5, v145
	v_or_b32_e32 v144, 0x6000, v144
	s_nop 0
	s_nop 1
	s_waitcnt vmcnt(40)
	ds_bpermute_b32 v112, v107, v112
	ds_bpermute_b32 v113, v107, v113
	ds_bpermute_b32 v114, v107, v114
	ds_bpermute_b32 v115, v107, v115
	s_waitcnt lgkmcnt(0)
	v_mfma_f32_16x16x32_bf16 v[58:61], v[112:115], v[70:73], v[58:61]
	global_load_dwordx2 v[112:113], v[196:197], off offset:320
	global_load_dwordx2 v[114:115], v[196:197], off offset:352
	v_lshl_add_u64 v[76:77], v[6:7], 0, v[4:5]
	s_nop 0
	s_nop 0
	s_nop 1
	s_waitcnt vmcnt(40)
	ds_bpermute_b32 v116, v107, v116
	ds_bpermute_b32 v117, v107, v117
	ds_bpermute_b32 v118, v107, v118
	ds_bpermute_b32 v119, v107, v119
	s_waitcnt lgkmcnt(0)
	v_mfma_f32_16x16x32_bf16 v[62:65], v[116:119], v[70:73], v[62:65]
	global_load_dwordx2 v[116:117], v[198:199], off offset:320
	global_load_dwordx2 v[118:119], v[198:199], off offset:352
	v_lshl_add_u64 v[76:77], v[6:7], 0, v[144:145]
	s_nop 0
	s_nop 0
	s_nop 1
	s_waitcnt vmcnt(40)
	ds_bpermute_b32 v120, v107, v120
	ds_bpermute_b32 v121, v107, v121
	ds_bpermute_b32 v122, v107, v122
	ds_bpermute_b32 v123, v107, v123
	s_waitcnt lgkmcnt(0)
	v_mfma_f32_16x16x32_bf16 v[66:69], v[120:123], v[70:73], v[66:69]
	global_load_dwordx2 v[120:121], v[200:201], off offset:384
	global_load_dwordx2 v[122:123], v[200:201], off offset:416
	v_cvt_pk_bf16_f32 v70, v94, v97
	v_cvt_pk_bf16_f32 v71, v98, v100
	v_cvt_pk_bf16_f32 v72, v102, v104
	v_cvt_pk_bf16_f32 v73, v105, v106
	s_nop 0
	s_nop 1
	s_waitcnt vmcnt(40)
	ds_bpermute_b32 v124, v107, v124
	ds_bpermute_b32 v125, v107, v125
	ds_bpermute_b32 v126, v107, v126
	ds_bpermute_b32 v127, v107, v127
	s_waitcnt lgkmcnt(0)
	v_mfma_f32_16x16x32_bf16 v[54:57], v[124:127], v[70:73], v[54:57]
	global_load_dwordx2 v[124:125], v[146:147], off offset:384
	global_load_dwordx2 v[126:127], v[146:147], off offset:416
	v_lshl_add_u64 v[76:77], v[78:79], 0, v[2:3]
	s_nop 0
	s_nop 0
	s_nop 1
	s_waitcnt vmcnt(40)
	ds_bpermute_b32 v128, v107, v128
	ds_bpermute_b32 v129, v107, v129
	ds_bpermute_b32 v130, v107, v130
	ds_bpermute_b32 v131, v107, v131
	s_waitcnt lgkmcnt(0)
	v_mfma_f32_16x16x32_bf16 v[58:61], v[128:131], v[70:73], v[58:61]
	global_load_dwordx2 v[128:129], v[196:197], off offset:384
	global_load_dwordx2 v[130:131], v[196:197], off offset:416
	v_lshl_add_u64 v[76:77], v[78:79], 0, v[4:5]
	s_nop 0
	s_nop 0
	s_nop 1
	s_waitcnt vmcnt(40)
	ds_bpermute_b32 v132, v107, v132
	ds_bpermute_b32 v133, v107, v133
	ds_bpermute_b32 v134, v107, v134
	ds_bpermute_b32 v135, v107, v135
	s_waitcnt lgkmcnt(0)
	v_mfma_f32_16x16x32_bf16 v[62:65], v[132:135], v[70:73], v[62:65]
	global_load_dwordx2 v[132:133], v[198:199], off offset:384
	global_load_dwordx2 v[134:135], v[198:199], off offset:416
	v_lshl_add_u64 v[76:77], v[78:79], 0, v[144:145]
	s_nop 0
	v_lshl_add_u64 v[78:79], v[6:7], 0, s[50:51]
	s_nop 0
	s_nop 1
	s_waitcnt vmcnt(40)
	ds_bpermute_b32 v136, v107, v136
	ds_bpermute_b32 v137, v107, v137
	ds_bpermute_b32 v138, v107, v138
	ds_bpermute_b32 v139, v107, v139
	s_waitcnt lgkmcnt(0)
; __device__ __forceinline__ f32x4 mfma16(bf16x8 a, bf16x8 b, f32x4 c) { return __builtin_amdgcn_mfma_f32_16x16x32_bf16(a, b, c, 0, 0, 0); }
; __device__ __forceinline__ void mem_attn(const Params& p, int layer, int task) {
;     ...
;   for (int k2 = 0; k2 < 8; k2++) {
;     bf16x8 pf;
;     unsigned q0 = pk2(st[2 * k2][0], st[2 * k2][1]), q1 = pk2(st[2 * k2][2], st[2 * k2][3]);
;     unsigned q2 = pk2(st[2 * k2 + 1][0], st[2 * k2 + 1][1]), q3 = pk2(st[2 * k2 + 1][2], st[2 * k2 + 1][3]);
;     pf[0] = (short)(q0 & 0xFFFF); pf[1] = (short)(q0 >> 16); pf[2] = (short)(q1 & 0xFFFF); pf[3] = (short)(q1 >> 16);
;     pf[4] = (short)(q2 & 0xFFFF); pf[5] = (short)(q2 >> 16); pf[6] = (short)(q3 & 0xFFFF); pf[7] = (short)(q3 >> 16);
; #pragma unroll
;     for (int mb = 0; mb < 4; mb++) {
;       const bf* vp = mvt + (size_t)(16 * mb + n16) * 256 + 32 * k2 + 4 * kq;
;       uint2 v0 = *(const uint2*)vp, v1 = *(const uint2*)(vp + 16);
;       bf16x8 af;
;       af[0] = (short)(v0.x & 0xFFFF); af[1] = (short)(v0.x >> 16); af[2] = (short)(v0.y & 0xFFFF); af[3] = (short)(v0.y >> 16);
;       af[4] = (short)(v1.x & 0xFFFF); af[5] = (short)(v1.x >> 16); af[6] = (short)(v1.y & 0xFFFF); af[7] = (short)(v1.y >> 16);
;       o[mb] = mfma16(af, pf, o[mb]);
;     }
	v_mfma_f32_16x16x32_bf16 v[66:69], v[136:139], v[70:73], v[66:69]
	global_load_dwordx2 v[136:137], v[200:201], off offset:448
	global_load_dwordx2 v[138:139], v[200:201], off offset:480
	v_cvt_pk_bf16_f32 v70, v85, v86
	v_cvt_pk_bf16_f32 v71, v87, v88
	v_cvt_pk_bf16_f32 v72, v89, v90
	v_cvt_pk_bf16_f32 v73, v91, v92
	s_nop 0
	s_nop 1
	s_waitcnt vmcnt(40)
	ds_bpermute_b32 v140, v107, v140
	ds_bpermute_b32 v141, v107, v141
	ds_bpermute_b32 v142, v107, v142
	ds_bpermute_b32 v143, v107, v143
	s_waitcnt lgkmcnt(0)
	v_mfma_f32_16x16x32_bf16 v[54:57], v[140:143], v[70:73], v[54:57]
	global_load_dwordx2 v[140:141], v[146:147], off offset:448
	global_load_dwordx2 v[142:143], v[146:147], off offset:480
	v_lshl_add_u64 v[76:77], v[78:79], 0, v[2:3]
	s_nop 0
	s_nop 0
	s_nop 1
	s_waitcnt vmcnt(40)
	ds_bpermute_b32 v148, v107, v148
	ds_bpermute_b32 v149, v107, v149
	ds_bpermute_b32 v150, v107, v150
	ds_bpermute_b32 v151, v107, v151
	s_waitcnt lgkmcnt(0)
	v_mfma_f32_16x16x32_bf16 v[58:61], v[148:151], v[70:73], v[58:61]
	global_load_dwordx2 v[148:149], v[196:197], off offset:448
	global_load_dwordx2 v[150:151], v[196:197], off offset:480
	v_lshl_add_u64 v[76:77], v[78:79], 0, v[4:5]
	s_nop 0
	s_nop 0
	s_nop 1
	s_waitcnt vmcnt(40)
	ds_bpermute_b32 v152, v107, v152
	ds_bpermute_b32 v153, v107, v153
	ds_bpermute_b32 v154, v107, v154
	ds_bpermute_b32 v155, v107, v155
	s_waitcnt lgkmcnt(0)
	v_mfma_f32_16x16x32_bf16 v[62:65], v[152:155], v[70:73], v[62:65]
	global_load_dwordx2 v[152:153], v[198:199], off offset:448
	global_load_dwordx2 v[154:155], v[198:199], off offset:480
	v_lshl_add_u64 v[76:77], v[78:79], 0, v[144:145]
	s_nop 0
	s_nop 0
	s_nop 1
	s_waitcnt vmcnt(40)
	ds_bpermute_b32 v156, v107, v156
	ds_bpermute_b32 v157, v107, v157
	ds_bpermute_b32 v158, v107, v158
	ds_bpermute_b32 v159, v107, v159
	s_waitcnt lgkmcnt(0)
	v_mfma_f32_16x16x32_bf16 v[66:69], v[156:159], v[70:73], v[66:69]
	s_nop 0
	s_nop 1
	s_waitcnt vmcnt(38)
	ds_bpermute_b32 v160, v107, v160
	ds_bpermute_b32 v161, v107, v161
	ds_bpermute_b32 v162, v107, v162
	ds_bpermute_b32 v163, v107, v163
	s_waitcnt lgkmcnt(0)
	v_mfma_f32_16x16x32_bf16 v[54:57], v[160:163], v[50:53], v[54:57]
	v_lshl_add_u64 v[72:73], v[48:49], 0, v[2:3]
	s_nop 0
	s_nop 0
	s_nop 1
	s_waitcnt vmcnt(36)
	ds_bpermute_b32 v164, v107, v164
	ds_bpermute_b32 v165, v107, v165
	ds_bpermute_b32 v166, v107, v166
	ds_bpermute_b32 v167, v107, v167
	s_waitcnt lgkmcnt(0)
	v_mfma_f32_16x16x32_bf16 v[58:61], v[164:167], v[50:53], v[58:61]
	v_lshl_add_u64 v[72:73], v[48:49], 0, v[4:5]
	s_nop 0
	v_lshl_add_u64 v[48:49], v[48:49], 0, v[144:145]
	s_nop 0
	s_nop 1
	s_waitcnt vmcnt(34)
	ds_bpermute_b32 v168, v107, v168
	ds_bpermute_b32 v169, v107, v169
	ds_bpermute_b32 v170, v107, v170
	ds_bpermute_b32 v171, v107, v171
	s_waitcnt lgkmcnt(0)
	v_mfma_f32_16x16x32_bf16 v[62:65], v[168:171], v[50:53], v[62:65]
	s_nop 0
	s_nop 0
	s_waitcnt vmcnt(32)
	ds_bpermute_b32 v172, v107, v172
	ds_bpermute_b32 v173, v107, v173
	ds_bpermute_b32 v174, v107, v174
	ds_bpermute_b32 v175, v107, v175
	s_waitcnt lgkmcnt(0)
	v_mfma_f32_16x16x32_bf16 v[48:51], v[172:175], v[50:53], v[66:69]
	s_nop 2
	v_lshl_add_u64 v[66:67], v[6:7], 0, s[70:71]
	s_waitcnt vmcnt(30)
	ds_bpermute_b32 v176, v107, v176
	ds_bpermute_b32 v177, v107, v177
	ds_bpermute_b32 v178, v107, v178
	ds_bpermute_b32 v179, v107, v179
	s_waitcnt lgkmcnt(0)
	v_mfma_f32_16x16x32_bf16 v[44:47], v[176:179], v[40:43], v[54:57]
	s_nop 2
	v_lshl_add_u64 v[54:55], v[66:67], 0, v[2:3]
	s_nop 0
	s_nop 0
	s_nop 1
	s_waitcnt vmcnt(28)
	ds_bpermute_b32 v180, v107, v180
	ds_bpermute_b32 v181, v107, v181
	ds_bpermute_b32 v182, v107, v182
	ds_bpermute_b32 v183, v107, v183
	s_waitcnt lgkmcnt(0)
	v_mfma_f32_16x16x32_bf16 v[52:55], v[180:183], v[40:43], v[58:61]
	s_nop 2
	v_lshl_add_u64 v[58:59], v[66:67], 0, v[4:5]
	s_nop 0
	s_nop 0
	s_nop 1
	s_waitcnt vmcnt(26)
	ds_bpermute_b32 v184, v107, v184
	ds_bpermute_b32 v185, v107, v185
	ds_bpermute_b32 v186, v107, v186
	ds_bpermute_b32 v187, v107, v187
	s_waitcnt lgkmcnt(0)
	v_mfma_f32_16x16x32_bf16 v[56:59], v[184:187], v[40:43], v[62:65]
	s_nop 2
	v_lshl_add_u64 v[62:63], v[66:67], 0, v[144:145]
	s_nop 0
	s_nop 0
	s_nop 0
	s_nop 0
	s_waitcnt vmcnt(24)
	ds_bpermute_b32 v188, v107, v188
	ds_bpermute_b32 v189, v107, v189
	ds_bpermute_b32 v190, v107, v190
	ds_bpermute_b32 v191, v107, v191
	s_waitcnt lgkmcnt(0)
	v_mfma_f32_16x16x32_bf16 v[40:43], v[188:191], v[40:43], v[48:51]
	v_lshl_add_u64 v[60:61], v[6:7], 0, s[0:1]
	s_nop 1
	v_lshl_add_u64 v[50:51], v[60:61], 0, v[4:5]
	s_mov_b64 s[0:1], 0x1c0
	s_waitcnt vmcnt(22)
	ds_bpermute_b32 v192, v107, v192
	ds_bpermute_b32 v193, v107, v193
	ds_bpermute_b32 v194, v107, v194
	ds_bpermute_b32 v195, v107, v195
	s_waitcnt lgkmcnt(0)
	v_mfma_f32_16x16x32_bf16 v[36:39], v[192:195], v[32:35], v[44:47]
	s_nop 2
	v_lshl_add_u64 v[46:47], v[60:61], 0, v[2:3]
	s_nop 0
	s_nop 0
	s_nop 0
	s_nop 0
	s_nop 1
	s_waitcnt vmcnt(20)
	ds_bpermute_b32 v108, v107, v108
	ds_bpermute_b32 v109, v107, v109
	ds_bpermute_b32 v110, v107, v110
	ds_bpermute_b32 v111, v107, v111
	s_waitcnt lgkmcnt(0)
	v_mfma_f32_16x16x32_bf16 v[44:47], v[108:111], v[32:35], v[52:55]
	s_nop 2
	v_lshl_add_u64 v[54:55], v[60:61], 0, v[144:145]
	s_nop 0
	s_nop 0
	s_nop 0
	s_nop 0
	s_nop 0
	s_waitcnt vmcnt(18)
	ds_bpermute_b32 v112, v107, v112
	ds_bpermute_b32 v113, v107, v113
	ds_bpermute_b32 v114, v107, v114
	ds_bpermute_b32 v115, v107, v115
	s_waitcnt lgkmcnt(0)
	v_mfma_f32_16x16x32_bf16 v[48:51], v[112:115], v[32:35], v[56:59]
	s_waitcnt vmcnt(16)
	ds_bpermute_b32 v116, v107, v116
	ds_bpermute_b32 v117, v107, v117
	ds_bpermute_b32 v118, v107, v118
	ds_bpermute_b32 v119, v107, v119
	s_waitcnt lgkmcnt(0)
; __device__ __forceinline__ float ozero() { float z = 0.f; asm volatile("" : "+v"(z)); return z; }
; __device__ __forceinline__ float bflo(unsigned u) { return __uint_as_float(u << 16); }
; __device__ __forceinline__ float bfhi(unsigned u) { return __uint_as_float(u & 0xFFFF0000u); }
; __device__ __forceinline__ float siluf_(float x) { return x * __builtin_amdgcn_rcpf(1.f + __expf(-x)); }
; __device__ __forceinline__ f32x4 mfma16(bf16x8 a, bf16x8 b, f32x4 c) { return __builtin_amdgcn_mfma_f32_16x16x32_bf16(a, b, c, 0, 0, 0); }
; __device__ __forceinline__ void mem_attn(const Params& p, int layer, int task) {
;     ...
;   const float rinv = 1.f / sum;
;   f32x4 o[4];
; #pragma unroll
;   for (int mb = 0; mb < 4; mb++) { const float z_ = ozero(); o[mb] = (f32x4){z_, z_, z_, z_}; }
; #pragma unroll
;   for (int k2 = 0; k2 < 8; k2++) {
;     bf16x8 pf;
;     unsigned q0 = pk2(st[2 * k2][0], st[2 * k2][1]), q1 = pk2(st[2 * k2][2], st[2 * k2][3]);
;     unsigned q2 = pk2(st[2 * k2 + 1][0], st[2 * k2 + 1][1]), q3 = pk2(st[2 * k2 + 1][2], st[2 * k2 + 1][3]);
;     pf[0] = (short)(q0 & 0xFFFF); pf[1] = (short)(q0 >> 16); pf[2] = (short)(q1 & 0xFFFF); pf[3] = (short)(q1 >> 16);
;     pf[4] = (short)(q2 & 0xFFFF); pf[5] = (short)(q2 >> 16); pf[6] = (short)(q3 & 0xFFFF); pf[7] = (short)(q3 >> 16);
; #pragma unroll
;     for (int mb = 0; mb < 4; mb++) {
;       const bf* vp = mvt + (size_t)(16 * mb + n16) * 256 + 32 * k2 + 4 * kq;
;       uint2 v0 = *(const uint2*)vp, v1 = *(const uint2*)(vp + 16);
;       bf16x8 af;
;       af[0] = (short)(v0.x & 0xFFFF); af[1] = (short)(v0.x >> 16); af[2] = (short)(v0.y & 0xFFFF); af[3] = (short)(v0.y >> 16);
;       af[4] = (short)(v1.x & 0xFFFF); af[5] = (short)(v1.x >> 16); af[6] = (short)(v1.y & 0xFFFF); af[7] = (short)(v1.y >> 16);
;       o[mb] = mfma16(af, pf, o[mb]);
;     }
;   }
;   const size_t tok = tok0 + n16;
; #pragma unroll
;   for (int mb = 0; mb < 4; mb++) {
;     const int d = 16 * mb + 4 * kq;
;     uint2 zz = *(const uint2*)(p.P + tok * PW + C_MEZ + h * 64 + d);
;     float v0 = o[mb][0] * rinv * siluf_(bflo(zz.x)), v1 = o[mb][1] * rinv * siluf_(bfhi(zz.x));
	v_mfma_f32_16x16x32_bf16 v[32:35], v[116:119], v[32:35], v[40:43]
	v_lshl_add_u64 v[52:53], v[6:7], 0, s[72:73]
	s_waitcnt vmcnt(14)
	ds_bpermute_b32 v120, v107, v120
	ds_bpermute_b32 v121, v107, v121
	ds_bpermute_b32 v122, v107, v122
	ds_bpermute_b32 v123, v107, v123
	s_waitcnt lgkmcnt(0)
	v_mfma_f32_16x16x32_bf16 v[28:31], v[120:123], v[24:27], v[36:39]
	s_nop 0
	v_lshl_add_u64 v[42:43], v[52:53], 0, v[4:5]
	s_nop 0
	v_lshl_add_u64 v[38:39], v[52:53], 0, v[2:3]
	s_nop 0
	s_nop 0
	s_nop 0
	s_nop 0
	s_nop 1
	s_waitcnt vmcnt(12)
	ds_bpermute_b32 v124, v107, v124
	ds_bpermute_b32 v125, v107, v125
	ds_bpermute_b32 v126, v107, v126
	ds_bpermute_b32 v127, v107, v127
	s_waitcnt lgkmcnt(0)
	v_mfma_f32_16x16x32_bf16 v[36:39], v[124:127], v[24:27], v[44:47]
	s_nop 2
	v_lshl_add_u64 v[46:47], v[52:53], 0, v[144:145]
	s_nop 0
	s_nop 0
	s_nop 0
	s_waitcnt vmcnt(10)
	ds_bpermute_b32 v128, v107, v128
	ds_bpermute_b32 v129, v107, v129
	ds_bpermute_b32 v130, v107, v130
	ds_bpermute_b32 v131, v107, v131
	s_waitcnt lgkmcnt(0)
	v_mfma_f32_16x16x32_bf16 v[40:43], v[128:131], v[24:27], v[48:51]
	s_nop 0
	s_waitcnt vmcnt(8)
	ds_bpermute_b32 v132, v107, v132
	ds_bpermute_b32 v133, v107, v133
	ds_bpermute_b32 v134, v107, v134
	ds_bpermute_b32 v135, v107, v135
	s_waitcnt lgkmcnt(0)
	v_mfma_f32_16x16x32_bf16 v[24:27], v[132:135], v[24:27], v[32:35]
	v_lshl_add_u64 v[44:45], v[6:7], 0, s[0:1]
	v_lshl_add_u64 v[2:3], v[44:45], 0, v[2:3]
	v_div_scale_f32 v23, s[0:1], v22, v22, 1.0
	v_cvt_pk_bf16_f32 v32, v8, v9
	s_nop 0
	s_nop 0
	v_cvt_pk_bf16_f32 v33, v10, v11
	v_cvt_pk_bf16_f32 v34, v12, v13
	v_cvt_pk_bf16_f32 v35, v14, v15
	s_mov_b64 s[0:1], 0x2ac0
	s_nop 0
	s_nop 0
	s_waitcnt vmcnt(6)
	ds_bpermute_b32 v136, v107, v136
	ds_bpermute_b32 v137, v107, v137
	ds_bpermute_b32 v138, v107, v138
	ds_bpermute_b32 v139, v107, v139
	s_waitcnt lgkmcnt(0)
	v_mfma_f32_16x16x32_bf16 v[12:15], v[136:139], v[32:35], v[28:31]
	s_nop 0
	s_waitcnt vmcnt(4)
	ds_bpermute_b32 v140, v107, v140
	ds_bpermute_b32 v141, v107, v141
	ds_bpermute_b32 v142, v107, v142
	ds_bpermute_b32 v143, v107, v143
	s_waitcnt lgkmcnt(0)
	v_mfma_f32_16x16x32_bf16 v[8:11], v[140:143], v[32:35], v[36:39]
	v_lshl_add_u64 v[2:3], v[44:45], 0, v[4:5]
	s_nop 0
	s_nop 0
	s_nop 1
	s_waitcnt vmcnt(2)
	ds_bpermute_b32 v148, v107, v148
	ds_bpermute_b32 v149, v107, v149
	ds_bpermute_b32 v150, v107, v150
	ds_bpermute_b32 v151, v107, v151
	s_waitcnt lgkmcnt(0)
	v_mfma_f32_16x16x32_bf16 v[4:7], v[148:151], v[32:35], v[40:43]
	v_lshl_add_u64 v[2:3], v[44:45], 0, v[144:145]
	s_nop 0
	s_nop 0
	s_nop 1
	s_waitcnt vmcnt(0)
	ds_bpermute_b32 v152, v107, v152
	ds_bpermute_b32 v153, v107, v153
	ds_bpermute_b32 v154, v107, v154
	ds_bpermute_b32 v155, v107, v155
	s_waitcnt lgkmcnt(0)
	v_mfma_f32_16x16x32_bf16 v[0:3], v[152:155], v[32:35], v[24:27]
	s_nop 2
	v_rcp_f32_e32 v24, v23
	s_nop 0
	v_fma_f32 v25, -v23, v24, 1.0
	v_fmac_f32_e32 v24, v25, v24
	v_div_scale_f32 v25, vcc, 1.0, v22, 1.0
	v_mul_f32_e32 v26, v25, v24
	v_fma_f32 v27, -v23, v26, v25
	v_fmac_f32_e32 v26, v27, v24
	v_fma_f32 v23, -v23, v26, v25
	v_div_fmas_f32 v23, v23, v24, v26
	v_lshl_add_u64 v[24:25], v[20:21], 0, v[18:19]
	v_lshl_add_u64 v[20:21], v[24:25], 0, s[0:1]
	v_add_co_u32_e32 v24, vcc, s2, v24
	v_div_fixup_f32 v22, v23, v22, 1.0
	s_nop 0
	v_addc_co_u32_e32 v25, vcc, 0, v25, vcc
	global_load_dwordx2 v[24:25], v[24:25], off offset:2752
	s_waitcnt vmcnt(0)
; __device__ __forceinline__ float bflo(unsigned u) { return __uint_as_float(u << 16); }
; __device__ __forceinline__ float bfhi(unsigned u) { return __uint_as_float(u & 0xFFFF0000u); }
; __device__ __forceinline__ float siluf_(float x) { return x * __builtin_amdgcn_rcpf(1.f + __expf(-x)); }
; __device__ __forceinline__ void mem_attn(const Params& p, int layer, int task) {
;     ...
;   const size_t tok = tok0 + n16;
; #pragma unroll
;   for (int mb = 0; mb < 4; mb++) {
;     const int d = 16 * mb + 4 * kq;
;     uint2 zz = *(const uint2*)(p.P + tok * PW + C_MEZ + h * 64 + d);
;     float v0 = o[mb][0] * rinv * siluf_(bflo(zz.x)), v1 = o[mb][1] * rinv * siluf_(bfhi(zz.x));
;     float v2 = o[mb][2] * rinv * siluf_(bflo(zz.y)), v3 = o[mb][3] * rinv * siluf_(bfhi(zz.y));
;     *(uint2*)(p.Y + tok * YW + Y_MEM + h * 64 + d) = make_uint2(pk2(v0, v1), pk2(v2, v3));
;   }
	v_lshlrev_b32_e32 v26, 16, v24
	v_mul_f32_e32 v23, 0xbfb8aa3b, v26
	v_exp_f32_e32 v23, v23
	v_and_b32_e32 v27, 0xffff0000, v24
	v_lshlrev_b32_e32 v24, 16, v25
	v_and_b32_e32 v25, 0xffff0000, v25
	v_add_f32_e32 v23, 1.0, v23
	v_rcp_f32_e32 v28, v23
	v_pk_mul_f32 v[12:13], v[22:23], v[12:13] op_sel_hi:[0,1]
	v_mul_f32_e32 v23, 0xbfb8aa3b, v27
	v_exp_f32_e32 v23, v23
	s_nop 0
	v_add_f32_e32 v23, 1.0, v23
	v_rcp_f32_e32 v29, v23
	v_mul_f32_e32 v23, 0xbfb8aa3b, v24
	v_exp_f32_e32 v23, v23
	v_pk_mul_f32 v[26:27], v[28:29], v[26:27]
	s_nop 0
	v_pk_mul_f32 v[12:13], v[12:13], v[26:27]
	v_add_f32_e32 v23, 1.0, v23
	v_rcp_f32_e32 v26, v23
	v_pk_mul_f32 v[14:15], v[22:23], v[14:15] op_sel_hi:[0,1]
	v_mul_f32_e32 v23, 0xbfb8aa3b, v25
	v_exp_f32_e32 v23, v23
	s_nop 0
	v_add_f32_e32 v23, 1.0, v23
	v_rcp_f32_e32 v27, v23
	v_pk_mul_f32 v[8:9], v[22:23], v[8:9] op_sel_hi:[0,1]
	v_pk_mul_f32 v[10:11], v[22:23], v[10:11] op_sel_hi:[0,1]
	v_pk_mul_f32 v[4:5], v[22:23], v[4:5] op_sel_hi:[0,1]
	v_pk_mul_f32 v[24:25], v[26:27], v[24:25]
	v_pk_mul_f32 v[6:7], v[22:23], v[6:7] op_sel_hi:[0,1]
	v_pk_mul_f32 v[14:15], v[14:15], v[24:25]
	v_cvt_pk_bf16_f32 v24, v12, v13
	v_mov_b64_e32 v[12:13], s[64:65]
	v_mad_u64_u32 v[12:13], s[0:1], v82, s97, v[12:13]
	v_lshl_add_u64 v[12:13], v[12:13], 0, v[16:17]
	v_cvt_pk_bf16_f32 v25, v14, v15
	v_lshl_add_u64 v[14:15], v[12:13], 0, v[18:19]
	s_mov_b64 s[0:1], 0x1000
	v_lshl_add_u64 v[12:13], v[14:15], 0, s[0:1]
	v_add_co_u32_e32 v14, vcc, s4, v14
	v_pk_mul_f32 v[0:1], v[22:23], v[0:1] op_sel_hi:[0,1]
	s_nop 0
	v_addc_co_u32_e32 v15, vcc, 0, v15, vcc
	global_store_dwordx2 v[14:15], v[24:25], off
	global_load_dwordx2 v[14:15], v[20:21], off offset:32
	v_pk_mul_f32 v[2:3], v[22:23], v[2:3] op_sel_hi:[0,1]
	s_mov_b64 s[0:1], 0
	s_waitcnt vmcnt(0)
	v_lshlrev_b32_e32 v16, 16, v14
	v_and_b32_e32 v17, 0xffff0000, v14
	v_mul_f32_e32 v14, 0xbfb8aa3b, v16
	v_exp_f32_e32 v14, v14
	s_nop 0
	v_add_f32_e32 v14, 1.0, v14
	v_rcp_f32_e32 v18, v14
	v_mul_f32_e32 v14, 0xbfb8aa3b, v17
	v_exp_f32_e32 v14, v14
	s_nop 0
	v_add_f32_e32 v14, 1.0, v14
	v_rcp_f32_e32 v19, v14
	v_lshlrev_b32_e32 v14, 16, v15
	v_and_b32_e32 v15, 0xffff0000, v15
	v_pk_mul_f32 v[16:17], v[18:19], v[16:17]
	s_nop 0
	v_pk_mul_f32 v[8:9], v[8:9], v[16:17]
	v_mul_f32_e32 v16, 0xbfb8aa3b, v14
	v_mul_f32_e32 v17, 0xbfb8aa3b, v15
	v_exp_f32_e32 v16, v16
	v_exp_f32_e32 v17, v17
	v_cvt_pk_bf16_f32 v8, v8, v9
	v_add_f32_e32 v16, 1.0, v16
	v_add_f32_e32 v17, 1.0, v17
	v_rcp_f32_e32 v16, v16
	v_rcp_f32_e32 v17, v17
	s_nop 0
	v_pk_mul_f32 v[14:15], v[16:17], v[14:15]
	s_nop 0
	v_pk_mul_f32 v[10:11], v[10:11], v[14:15]
	s_nop 0
	v_cvt_pk_bf16_f32 v9, v10, v11
	global_store_dwordx2 v[12:13], v[8:9], off offset:32
	global_load_dwordx2 v[8:9], v[20:21], off offset:64
	s_waitcnt vmcnt(0)
	v_lshlrev_b32_e32 v10, 16, v8
	v_and_b32_e32 v11, 0xffff0000, v8
	v_mul_f32_e32 v8, 0xbfb8aa3b, v10
	v_exp_f32_e32 v8, v8
	s_nop 0
	v_add_f32_e32 v8, 1.0, v8
	v_rcp_f32_e32 v14, v8
	v_mul_f32_e32 v8, 0xbfb8aa3b, v11
	v_exp_f32_e32 v8, v8
	s_nop 0
	v_add_f32_e32 v8, 1.0, v8
	v_rcp_f32_e32 v15, v8
	v_lshlrev_b32_e32 v8, 16, v9
	v_and_b32_e32 v9, 0xffff0000, v9
	v_pk_mul_f32 v[10:11], v[14:15], v[10:11]
	s_nop 0
	v_pk_mul_f32 v[4:5], v[4:5], v[10:11]
	v_mul_f32_e32 v10, 0xbfb8aa3b, v8
	v_mul_f32_e32 v11, 0xbfb8aa3b, v9
	v_exp_f32_e32 v10, v10
	v_exp_f32_e32 v11, v11
	v_cvt_pk_bf16_f32 v4, v4, v5
	v_add_f32_e32 v10, 1.0, v10
	v_add_f32_e32 v11, 1.0, v11
	v_rcp_f32_e32 v10, v10
	v_rcp_f32_e32 v11, v11
	s_nop 0
	v_pk_mul_f32 v[8:9], v[10:11], v[8:9]
	s_nop 0
	v_pk_mul_f32 v[6:7], v[6:7], v[8:9]
	s_nop 0
	v_cvt_pk_bf16_f32 v5, v6, v7
	global_store_dwordx2 v[12:13], v[4:5], off offset:64
	global_load_dwordx2 v[4:5], v[20:21], off offset:96
	s_waitcnt vmcnt(0)
	v_lshlrev_b32_e32 v6, 16, v4
	v_and_b32_e32 v7, 0xffff0000, v4
	v_mul_f32_e32 v4, 0xbfb8aa3b, v6
	v_exp_f32_e32 v4, v4
	s_nop 0
	v_add_f32_e32 v4, 1.0, v4
	v_rcp_f32_e32 v8, v4
	v_mul_f32_e32 v4, 0xbfb8aa3b, v7
	v_exp_f32_e32 v4, v4
	s_nop 0
	v_add_f32_e32 v4, 1.0, v4
	v_rcp_f32_e32 v9, v4
	v_lshlrev_b32_e32 v4, 16, v5
	v_and_b32_e32 v5, 0xffff0000, v5
	v_pk_mul_f32 v[6:7], v[8:9], v[6:7]
	s_nop 0
	v_pk_mul_f32 v[0:1], v[0:1], v[6:7]
	v_mul_f32_e32 v6, 0xbfb8aa3b, v4
	v_mul_f32_e32 v7, 0xbfb8aa3b, v5
	v_exp_f32_e32 v6, v6
	v_exp_f32_e32 v7, v7
	v_cvt_pk_bf16_f32 v0, v0, v1
	v_add_f32_e32 v6, 1.0, v6
	v_add_f32_e32 v7, 1.0, v7
	v_rcp_f32_e32 v6, v6
	v_rcp_f32_e32 v7, v7
	s_nop 0
	v_pk_mul_f32 v[4:5], v[6:7], v[4:5]
	s_nop 0
	v_pk_mul_f32 v[2:3], v[2:3], v[4:5]
	s_nop 0
	v_cvt_pk_bf16_f32 v1, v2, v3
	global_store_dwordx2 v[12:13], v[0:1], off offset:96
